# P3 delta items: beta/log-decay scan block computed for all 8 items up front (one item per wave) into LDS staging; wave 0 only copies in loop
# speedup vs baseline: 1.0622x; 1.0033x over previous
.LBB0_309:
	v_writelane_b32 v250, s97, 9
	v_writelane_b32 v250, s66, 6
	s_andn2_b64 vcc, exec, s[0:1]
	s_nop 0
	v_writelane_b32 v250, s67, 7
	v_writelane_b32 v250, s95, 8
	s_cbranch_vccnz .LBB0_460
	v_mbcnt_lo_u32_b32 v30, -1, 0
	v_mbcnt_hi_u32_b32 v36, -1, v30
	v_and_b32_e32 v31, 64, v36
	v_xor_b32_e32 v30, 1, v36
	v_add_u32_e32 v32, 64, v31
	v_cmp_lt_i32_e32 vcc, v30, v32
	s_movk_i32 s0, 0x27f
	s_add_i32 s3, 0, 0x4400
	v_cndmask_b32_e32 v37, v36, v30, vcc
	v_xor_b32_e32 v30, 2, v36
	v_cmp_lt_i32_e32 vcc, v30, v32
	s_cmp_lt_u32 s38, 64
	v_lshrrev_b32_e32 v56, 4, v1
	v_cndmask_b32_e32 v38, v36, v30, vcc
	v_xor_b32_e32 v30, 4, v36
	v_cmp_lt_i32_e32 vcc, v30, v32
	v_lshlrev_b32_e32 v58, 2, v56
	v_lshlrev_b32_e32 v86, 3, v0
	v_cndmask_b32_e32 v39, v36, v30, vcc
	v_xor_b32_e32 v30, 8, v36
	v_cmp_lt_i32_e32 vcc, v30, v32
	v_and_b32_e32 v57, 56, v86
	v_mov_b32_e32 v66, 0xffff
	v_cndmask_b32_e32 v40, v36, v30, vcc
	v_add_u32_e32 v30, -1, v36
	v_cmp_lt_i32_e32 vcc, v30, v31
	v_mov_b32_e32 v67, 0xffff0000
	v_or_b32_e32 v63, 2, v57
	v_cndmask_b32_e32 v41, v30, v36, vcc
	v_add_u32_e32 v30, -2, v36
	v_cmp_lt_i32_e32 vcc, v30, v31
	v_or_b32_e32 v65, 4, v57
	v_or_b32_e32 v80, 6, v57
	v_cndmask_b32_e32 v42, v30, v36, vcc
	v_add_u32_e32 v30, -4, v36
	v_cmp_lt_i32_e32 vcc, v30, v31
	v_lshlrev_b32_e32 v90, 2, v1
	v_lshrrev_b32_e32 v85, 2, v0
	v_cndmask_b32_e32 v43, v30, v36, vcc
	v_add_u32_e32 v30, -8, v36
	v_cmp_lt_i32_e32 vcc, v30, v31
	v_and_b32_e32 v85, 0x78, v85
	v_lshlrev_b32_e32 v146, 4, v0
	v_cndmask_b32_e32 v44, v30, v36, vcc
	v_add_u32_e32 v30, -16, v36
	v_cmp_lt_i32_e32 vcc, v30, v31
	v_lshlrev_b32_e32 v158, 2, v37
	v_mov_b32_e32 v37, 0x80
	v_cndmask_b32_e32 v45, v30, v36, vcc
	v_subrev_u32_e32 v30, 32, v36
	v_cmp_lt_i32_e32 vcc, v30, v31
	v_mov_b32_e32 v31, 0xfffffb80
	v_mov_b32_e32 v89, s3
	v_cndmask_b32_e32 v46, v30, v36, vcc
	v_and_b32_e32 v30, 63, v36
	v_cmp_ne_u32_e32 vcc, 63, v30
	v_lshl_or_b32 v173, v36, 2, v37
	v_mov_b32_e32 v37, 0x2000
	v_addc_co_u32_e32 v47, vcc, 0, v36, vcc
	v_cmp_gt_u32_e32 vcc, 62, v30
	v_lshlrev_b32_e32 v163, 2, v42
	v_lshlrev_b32_e32 v166, 2, v45
	v_cndmask_b32_e64 v48, 0, 2, vcc
	v_cmp_gt_u32_e32 vcc, 60, v30
	v_add_lshl_u32 v169, v48, v36, 2
	v_bfe_u32 v45, v0, 4, 1
	v_cndmask_b32_e64 v49, 0, 4, vcc
	v_cmp_gt_u32_e32 vcc, 56, v30
	v_add_lshl_u32 v170, v49, v36, 2
	v_lshlrev_b32_e32 v165, 2, v44
	v_cndmask_b32_e64 v50, 0, 8, vcc
	v_cmp_gt_u32_e32 vcc, 48, v30
	v_mov_b32_e32 v30, 0xba00
	v_add_lshl_u32 v171, v50, v36, 2
	v_cndmask_b32_e64 v51, 0, 16, vcc
	v_cmp_lt_u32_e32 vcc, s0, v0
	s_movk_i32 s0, 0x7f
	v_add_lshl_u32 v172, v51, v36, 2
	v_cndmask_b32_e32 v52, 0, v30, vcc
	v_cndmask_b32_e32 v53, 0, v31, vcc
	v_cmp_lt_u32_e32 vcc, s0, v0
	s_cselect_b64 s[0:1], -1, 0
	v_writelane_b32 v250, s0, 10
	v_cndmask_b32_e32 v54, 0, v30, vcc
	v_and_b32_e32 v30, 15, v0
	v_writelane_b32 v250, s1, 11
	s_add_u32 s0, s74, 0xb4000
	s_addc_u32 s1, s75, 0
	v_writelane_b32 v250, s0, 12
	s_bfe_u32 s33, s38, 0x20006
	s_lshl_b32 s41, s33, 4
	v_writelane_b32 v250, s1, 13
	s_lshr_b32 s0, s38, 8
	s_mul_i32 s1, s0, 0xba00
	s_add_i32 s39, s1, 0
	s_add_i32 s40, s39, 0x8c00
	s_mul_i32 s1, s33, 0x500
	s_mul_i32 s0, s0, 0xffff4700
	s_add_i32 s42, s39, s0
	s_add_i32 s47, s40, s1
	s_cmpk_gt_u32 s38, 0xff
	s_cselect_b64 s[0:1], -1, 0
	v_or_b32_e32 v32, s41, v58
	v_writelane_b32 v250, s0, 14
	s_cmpk_lt_u32 s38, 0x100
	v_cmp_gt_u32_e64 s[4:5], v30, v32
	v_writelane_b32 v250, s1, 15
	s_cselect_b64 s[0:1], -1, 0
	s_xor_b64 s[6:7], s[0:1], s[4:5]
	v_writelane_b32 v250, s6, 16
	v_or_b32_e32 v59, 1, v32
	v_or_b32_e32 v68, 2, v32
	v_writelane_b32 v250, s7, 17
	v_cmp_gt_u32_e64 s[6:7], v30, v59
	s_xor_b64 s[8:9], s[0:1], s[6:7]
	v_writelane_b32 v250, s8, 18
	v_or_b32_e32 v69, 3, v32
	v_or_b32_e32 v35, 16, v30
	v_writelane_b32 v250, s9, 19
	v_cmp_gt_u32_e64 s[8:9], v30, v68
	s_xor_b64 s[10:11], s[0:1], s[8:9]
	v_writelane_b32 v250, s10, 20
	v_cndmask_b32_e32 v55, 0, v31, vcc
	s_lshl_b32 s2, s33, 5
	v_writelane_b32 v250, s11, 21
	v_cmp_gt_u32_e64 s[10:11], v30, v69
	s_xor_b64 s[12:13], s[0:1], s[10:11]
	v_writelane_b32 v250, s12, 22
	v_cmp_eq_u32_e32 vcc, 1, v1
	s_add_i32 s43, s39, s2
	v_writelane_b32 v250, s13, 23
	v_cmp_gt_u32_e64 s[12:13], v35, v32
	s_xor_b64 s[14:15], s[0:1], s[12:13]
	v_writelane_b32 v250, s14, 24
	s_add_i32 s44, 0, 0x21a00
	v_cndmask_b32_e64 v71, 0, 1.0, vcc
	v_writelane_b32 v250, s15, 25
	v_cmp_gt_u32_e64 s[14:15], v35, v59
	s_xor_b64 s[16:17], s[0:1], s[14:15]
	v_writelane_b32 v250, s16, 26
	v_cmp_eq_u32_e32 vcc, 2, v1
	v_or_b32_e32 v34, 32, v30
	v_writelane_b32 v250, s17, 27
	v_cmp_gt_u32_e64 s[16:17], v35, v68
	s_xor_b64 s[18:19], s[0:1], s[16:17]
	v_writelane_b32 v250, s18, 28
	v_cndmask_b32_e64 v70, 0, 1.0, vcc
	v_cmp_eq_u32_e32 vcc, 3, v1
	v_writelane_b32 v250, s19, 29
	v_cmp_gt_u32_e64 s[18:19], v35, v69
	s_xor_b64 s[20:21], s[0:1], s[18:19]
	v_writelane_b32 v250, s20, 30
	s_cmp_eq_u32 s33, 1
	v_cndmask_b32_e64 v87, 0, 1.0, vcc
	v_writelane_b32 v250, s21, 31
	s_cselect_b64 s[20:21], -1, 0
	v_cmp_eq_u32_e32 vcc, 4, v1
	v_writelane_b32 v250, s20, 32
	v_cmp_gt_u32_e64 s[26:27], v34, v69
	v_cndmask_b32_e64 v73, 0, 1.0, vcc
	v_cmp_eq_u32_e32 vcc, 5, v1
	v_writelane_b32 v250, s21, 33
	v_cmp_gt_u32_e64 s[20:21], v34, v32
	v_cndmask_b32_e64 v72, 0, 1.0, vcc
	v_cmp_eq_u32_e32 vcc, 6, v1
	s_xor_b64 s[22:23], s[0:1], s[20:21]
	v_writelane_b32 v250, s22, 34
	v_cndmask_b32_e64 v113, 0, 1.0, vcc
	v_cmp_eq_u32_e32 vcc, 7, v1
	v_writelane_b32 v250, s23, 35
	v_cmp_gt_u32_e64 s[22:23], v34, v59
	v_cndmask_b32_e64 v117, 0, 1.0, vcc
	v_cmp_eq_u32_e32 vcc, 8, v1
	s_xor_b64 s[24:25], s[0:1], s[22:23]
	v_writelane_b32 v250, s24, 36
	v_cndmask_b32_e64 v75, 0, 1.0, vcc
	v_cmp_eq_u32_e32 vcc, 9, v1
	v_writelane_b32 v250, s25, 37
	v_cmp_gt_u32_e64 s[24:25], v34, v68
	v_cndmask_b32_e64 v74, 0, 1.0, vcc
	v_cmp_eq_u32_e32 vcc, 10, v1
	v_or_b32_e32 v33, 48, v30
	s_xor_b64 s[56:57], s[0:1], s[24:25]
	v_cndmask_b32_e64 v144, 0, 1.0, vcc
	v_cmp_eq_u32_e32 vcc, 11, v1
	s_xor_b64 s[58:59], s[0:1], s[26:27]
	s_cmp_eq_u32 s33, 2
	v_cndmask_b32_e64 v145, 0, 1.0, vcc
	v_cmp_eq_u32_e32 vcc, 12, v1
	v_cmp_gt_u32_e64 s[28:29], v33, v32
	v_cmp_gt_u32_e64 s[30:31], v33, v59
	v_cndmask_b32_e64 v77, 0, 1.0, vcc
	v_cmp_eq_u32_e32 vcc, 13, v1
	v_cmp_gt_u32_e64 s[34:35], v33, v68
	v_cmp_gt_u32_e64 s[36:37], v33, v69
	v_cndmask_b32_e64 v79, 0, 1.0, vcc
	v_cmp_eq_u32_e32 vcc, 14, v1
	v_lshrrev_b32_e32 v31, 3, v0
	s_cselect_b64 s[60:61], -1, 0
	s_xor_b64 s[62:63], s[0:1], s[28:29]
	s_xor_b64 s[64:65], s[0:1], s[30:31]
	s_xor_b64 s[90:91], s[0:1], s[34:35]
	v_cndmask_b32_e64 v78, 0, 1.0, vcc
	v_cmp_eq_u32_e32 vcc, 15, v1
	s_xor_b64 s[94:95], s[0:1], s[36:37]
	s_mul_i32 s45, s33, 0x300
	v_cndmask_b32_e64 v76, 0, 1.0, vcc
	v_cmp_gt_u32_e32 vcc, v57, v31
	s_cmp_eq_u32 s33, 3
	s_cselect_b64 s[96:97], -1, 0
	v_cndmask_b32_e64 v60, v66, 0, vcc
	v_cmp_lt_u32_e32 vcc, v57, v31
	s_add_i32 s45, s40, s45
	s_add_u32 s84, s74, 0x39c4000
	v_cndmask_b32_e32 v61, 0, v67, vcc
	v_cmp_gt_u32_e32 vcc, v63, v31
	s_addc_u32 s85, s75, 0
	s_bfe_u32 s46, s38, 0x10006
	v_cndmask_b32_e64 v62, v66, 0, vcc
	v_cmp_lt_u32_e32 vcc, v63, v31
	v_readlane_b32 s54, v250, 6
	s_bitcmp1_b32 s38, 6
	v_cndmask_b32_e32 v63, 0, v67, vcc
	v_cmp_gt_u32_e32 vcc, v65, v31
	v_readlane_b32 s55, v250, 7
	s_cselect_b64 s[86:87], -1, 0
	v_cndmask_b32_e64 v64, v66, 0, vcc
	v_cmp_lt_u32_e32 vcc, v65, v31
	s_ashr_i32 s55, s54, 31
	s_lshl_b64 s[0:1], s[54:55], 10
	v_cndmask_b32_e32 v65, 0, v67, vcc
	v_cmp_gt_u32_e32 vcc, v80, v31
	v_mov_b32_e32 v81, s1
	v_lshlrev_b32_e32 v84, 10, v30
	v_cndmask_b32_e64 v66, v66, 0, vcc
	v_cmp_lt_u32_e32 vcc, v80, v31
	v_or_b32_e32 v80, s0, v90
	s_lshl_b64 s[0:1], s[54:55], 14
	v_or3_b32 v84, s0, v84, v85
	v_mov_b32_e32 v85, s1
	v_or_b32_e32 v82, s0, v146
	v_mov_b32_e32 v83, s1
	v_lshl_add_u64 v[84:85], s[72:73], 0, v[84:85]
	s_mov_b64 s[0:1], 0x2000200
	v_lshl_add_u64 v[84:85], v[84:85], 0, s[0:1]
	v_or_b32_e32 v92, s41, v30
	s_movk_i32 s0, 0x110
	v_lshlrev_b32_e32 v151, 7, v59
	v_lshlrev_b32_e32 v59, 6, v0
	v_mad_u32_u24 v88, v92, s0, 0
	v_and_b32_e32 v59, 0x400, v59
	s_movk_i32 s0, 0x78
	v_and_or_b32 v154, v86, s0, v59
	v_mov_b32_e32 v86, s40
	s_movk_i32 s0, 0x50
	v_writelane_b32 v250, s47, 38
	v_mov_b32_e32 v59, s47
	v_lshl_or_b32 v98, s46, 4, v30
	v_mad_u32_u24 v59, v30, s0, v59
	v_mad_u32_u24 v157, v98, s0, v86
	v_readlane_b32 s0, v250, 9
	s_lshl_b32 s0, s0, 3
	s_and_b32 s0, s0, 16
	v_or_b32_e32 v99, s0, v58
	s_or_b32 s0, s0, 32
	v_or_b32_e32 v100, s0, v30
	v_or_b32_e32 v58, s0, v58
	v_sub_co_u32_e64 v101, s[0:1], s33, 1
	v_lshlrev_b32_e32 v102, 5, v101
	s_lshl_b32 s3, s46, 5
	v_add_u32_e32 v36, v0, v53
	v_lshlrev_b32_e32 v91, 1, v30
	v_mov_b32_e32 v97, s39
	v_add_u32_e32 v103, s39, v102
	s_add_i32 s39, s39, s3
	v_lshl_add_u32 v42, v36, 4, v37
	v_add_u32_e32 v36, v55, v0
	v_mov_b32_e32 v37, 0x4000
	v_lshl_add_u32 v44, v36, 4, v37
	v_lshlrev_b32_e32 v86, 3, v30
	v_add_u32_e32 v37, s39, v91
	v_cmp_eq_u32_e64 s[38:39], 0, v45
	v_lshlrev_b32_e32 v150, 7, v32
	v_lshlrev_b32_e32 v152, 7, v68
	v_lshlrev_b32_e32 v153, 7, v69
	v_lshl_or_b32 v174, v45, 10, v86
	v_cndmask_b32_e64 v45, 0, v89, s[38:39]
	v_lshl_add_u32 v147, v30, 2, s42
	v_add_u32_e32 v68, s44, v150
	v_add_u32_e32 v69, s44, v151
	v_add_u32_e32 v93, s44, v152
	v_add_u32_e32 v94, s44, v153
	v_mad_u32_u24 v156, v30, 48, s45
	v_lshlrev_b32_e32 v159, 2, v38
	s_add_i32 s3, 0, 0x1b200
	v_lshl_or_b32 v38, v101, 4, v30
	v_lshl_add_u32 v45, v30, 4, v45
	v_mul_u32_u24_e32 v48, 0x110, v30
	v_mul_u32_u24_e32 v50, 0x90, v30
	v_lshlrev_b32_e32 v30, 1, v35
	v_add_u32_e32 v96, s41, v1
	v_lshlrev_b32_e32 v160, 2, v39
	v_mov_b32_e32 v39, s3
	s_movk_i32 s3, 0x90
	v_add_u32_e32 v186, v68, v30
	v_add_u32_e32 v187, v69, v30
	v_add_u32_e32 v188, v93, v30
	v_add_u32_e32 v189, v94, v30
	v_lshlrev_b32_e32 v30, 1, v34
	v_lshlrev_b32_e32 v168, 2, v47
	v_mad_u32_u24 v47, v96, s3, v97
	v_mad_u32_u24 v175, v92, s3, v97
	v_mad_i32_i24 v176, v38, s3, v97
	v_add_u32_e32 v190, v68, v30
	v_add_u32_e32 v191, v69, v30
	v_add_u32_e32 v192, v93, v30
	v_add_u32_e32 v193, v94, v30
	v_lshlrev_b32_e32 v30, 1, v33
	v_lshlrev_b32_e32 v161, 2, v40
	v_mad_u32_u24 v40, v100, s3, v97
	v_mad_u32_u24 v177, v98, s3, v97
	v_mad_u32_u24 v38, v31, s3, 0
	v_mad_u32_u24 v39, v31, s3, v39
	v_add_u32_e32 v194, v68, v30
	v_add_u32_e32 v195, v69, v30
	v_add_u32_e32 v196, v93, v30
	v_add_u32_e32 v197, v94, v30
	v_add_u32_e32 v30, s2, v175
	v_add_u32_e32 v33, s2, v176
	v_add_u32_e32 v198, s2, v47
	v_cmp_eq_u32_e64 s[2:3], 0, v1
	v_lshl_add_u32 v95, v1, 1, s43
	s_mulk_i32 s33, 0x900
	v_writelane_b32 v250, s2, 39
	v_add_u32_e32 v184, 0, v90
	v_lshlrev_b32_e32 v155, 3, v56
	v_writelane_b32 v250, s3, 40
	v_cndmask_b32_e64 v90, 0, 1.0, s[2:3]
	s_add_i32 s2, s54, s70
	v_add_u32_e32 v178, s33, v95
	s_lshl_b32 s33, s2, 7
	s_movk_i32 s2, 0x300
	v_lshl_add_u32 v148, v32, 2, s42
	v_add_u32_e32 v56, s43, v155
	v_cmp_gt_u32_e64 s[42:43], s2, v0
	s_movk_i32 s2, 0x100
	v_add_u32_e32 v149, s44, v91
	v_cmp_gt_u32_e64 s[44:45], s2, v0
	s_mov_b32 s2, s54
	v_writelane_b32 v250, s2, 6
	v_or_b32_e32 v183, 3, v31
	s_mov_b32 s81, 0
	v_writelane_b32 v250, s3, 7
	v_cmp_gt_u32_e64 s[2:3], 2, v1
	v_lshlrev_b32_e32 v167, 2, v46
	v_mov_b32_e32 v46, 0x3db504f3
	v_writelane_b32 v250, s2, 41
	v_and_b32_e32 v180, 60, v31
	v_mul_u32_u24_e32 v31, 0x110, v183
	v_writelane_b32 v250, s3, 42
	v_cmp_gt_u32_e64 s[2:3], 4, v1
	v_and_b32_e32 v185, 48, v0
	s_mov_b32 s82, s81
	v_writelane_b32 v250, s2, 43
	s_mov_b32 s83, s81
	v_cndmask_b32_e32 v67, 0, v67, vcc
	v_writelane_b32 v250, s3, 44
	v_cmp_gt_u32_e64 s[2:3], 8, v1
	v_lshlrev_b32_e32 v162, 2, v41
	v_lshlrev_b32_e32 v164, 2, v43
	v_writelane_b32 v250, s2, 45
	v_add_u32_e32 v41, 0, v52
	v_add_u32_e32 v43, 0, v54
	v_writelane_b32 v250, s3, 46
	v_cmp_eq_u32_e64 s[2:3], 63, v1
	v_and_b32_e32 v36, 16, v0
	v_cndmask_b32_e64 v179, 1.0, v46, s[38:39]
	v_writelane_b32 v250, s2, 47
	v_mov_b32_e32 v89, 0
	v_mul_u32_u24_e32 v46, 0x110, v180
	v_writelane_b32 v250, s3, 48
	v_cmp_gt_u32_e64 s[2:3], 62, v1
	v_add_u32_e32 v49, 0, v185
	v_add_u32_e32 v34, v103, v91
	v_writelane_b32 v250, s2, 49
	v_mul_u32_u24_e32 v32, 0x90, v32
	v_lshlrev_b32_e32 v35, 1, v99
	v_writelane_b32 v250, s3, 50
	v_cmp_gt_u32_e64 s[2:3], 60, v1
	v_mul_u32_u24_e32 v47, 0x90, v58
	v_lshlrev_b32_e32 v51, 1, v58
	v_writelane_b32 v250, s2, 51
	v_lshlrev_b32_e32 v52, 1, v57
	s_ashr_i32 s71, s70, 31
	v_writelane_b32 v250, s3, 52
	v_cmp_gt_u32_e64 s[2:3], 56, v1
	s_mov_b32 s80, s81
	v_mov_b64_e32 v[236:237], s[82:83]
	v_writelane_b32 v250, s2, 53
	v_add_u32_e32 v211, v45, v31
	v_or_b32_e32 v181, 1, v180
	v_writelane_b32 v250, s3, 54
	v_cmp_gt_u32_e64 s[2:3], 48, v1
	v_or_b32_e32 v182, 2, v180
	v_cvt_pk_bf16_f32 v199, v90, s0
	v_add_u32_e32 v200, v102, v185
	v_or_b32_e32 v201, v60, v61
	v_bitop3_b32 v202, v60, v61, v60 bitop3:3
	v_or_b32_e32 v203, v62, v63
	v_bitop3_b32 v204, v62, v63, v62 bitop3:3
	v_or_b32_e32 v205, v64, v65
	v_bitop3_b32 v206, v64, v65, v64 bitop3:3
	v_or_b32_e32 v207, v66, v67
	v_bitop3_b32 v208, v66, v67, v66 bitop3:3
	v_mov_b32_e32 v92, v90
	v_mov_b32_e32 v93, v90
	v_mov_b64_e32 v[234:235], s[80:81]
	v_add_u32_e32 v209, v41, v42
	v_add_u32_e32 v210, v43, v44
	v_mov_b32_e32 v212, 0x3ecc95a3
	v_add_u32_e32 v213, v88, v185
	v_add_u32_e32 v214, v49, v48
	v_add_u32_e32 v215, v30, v185
	v_add_u32_e32 v216, v34, v32
	v_add_u32_e32 v217, v33, v155
	v_add_u32_e32 v218, v40, v185
	v_add_u32_e32 v219, v157, v35
	v_add_u32_e32 v220, v37, v47
	v_add_u32_e32 v221, v177, v51
	v_add_u32_e32 v222, v38, v52
	v_add_u32_e32 v223, v39, v52
	v_mov_b32_e32 v30, v89
	v_mov_b32_e32 v31, v89
	v_mov_b32_e32 v32, v89
	v_mov_b32_e32 v33, v89
	v_add_u32_e32 v224, v45, v46
	v_mov_b32_e32 v94, 0x3f317218
	v_mov_b32_e32 v225, 0x7f800000
	v_mov_b32_e32 v226, 0x7fc00000
	v_mov_b32_e32 v227, 0xff800000
	v_add_u32_e32 v228, v56, v50
	v_add_u32_e32 v229, v59, v185
	s_lshl_b32 s40, s70, 7
	s_lshl_b32 s41, s54, 3
	s_lshl_b32 s48, s70, 3
	s_add_i32 s49, 0, 0x18e00
	s_movk_i32 s50, 0x3000
	s_mov_b32 s51, 0xbfb8aa3b
	s_mov_b32 s52, 0x800000
	s_mov_b32 s53, s54
	v_cmp_ne_u32_e64 s[46:47], 0, v36
	v_cmp_gt_u32_e64 s[54:55], 16, v1
	v_writelane_b32 v250, s2, 55
	v_cmp_gt_u32_e64 s[66:67], 32, v1
	s_lshl_b64 s[82:83], s[70:71], 10
	s_lshl_b64 s[92:93], s[70:71], 14
	v_writelane_b32 v250, s3, 56
	v_readfirstlane_b32 s2, v0
	s_lshr_b32 s2, s2, 6
	s_mul_i32 s3, s2, s48
	s_add_i32 s3, s3, s41
	s_and_b32 s71, s3, 0xffffffc0
	s_and_b32 s68, s53, 7
	s_mul_i32 s88, s2, s82
	s_mov_b32 s89, 0
	s_lshl_b32 s3, s2, 10
	s_add_i32 s3, s3, 0x1c200
	v_lshl_add_u64 v[56:57], v[80:81], 0, s[88:89]
	v_add_u32_e32 v58, s3, v184
	v_or_b32_e32 v34, s71, v1
	v_ashrrev_i32_e32 v35, 31, v34
	v_readlane_b32 s2, v250, 12
	v_lshlrev_b64 v[34:35], 7, v[34:35]
	v_readlane_b32 s3, v250, 13
	s_lshl_b32 s80, s68, 2
	v_mov_b32_e32 v38, s80
	v_lshl_add_u64 v[34:35], s[2:3], 0, v[34:35]
	v_readlane_b32 s2, v250, 4
	v_readlane_b32 s3, v250, 5
	v_lshl_add_u64 v[34:35], v[34:35], 0, s[80:81]
	s_nop 3
	global_load_dword v39, v38, s[2:3]
	global_load_dword v37, v[34:35], off
	global_load_dword v40, v[34:35], off offset:64
	global_load_dword v36, v[34:35], off offset:32
	s_nop 0
	global_load_dword v38, v38, s[78:79]
	s_add_u32 s68, s78, s80
	s_addc_u32 s69, s79, 0
	s_add_u32 s88, s2, s80
	s_mov_b32 s2, 0x41a00000
	s_addc_u32 s89, s3, 0
	s_waitcnt vmcnt(2)
	v_add_f32_e32 v39, v40, v39
	v_cmp_nlt_f32_e32 vcc, s2, v39
	s_and_saveexec_b64 s[2:3], vcc
	s_cbranch_execz .Lp3pre_330
	v_mul_f32_e32 v39, 0x3fb8aa3b, v39
	v_exp_f32_e32 v39, v39
	s_mov_b32 s71, 0x3f2aaaab
	v_add_f32_e32 v42, 1.0, v39
	v_frexp_mant_f32_e32 v44, v42
	v_cvt_f64_f32_e32 v[40:41], v42
	v_frexp_exp_i32_f64_e32 v40, v[40:41]
	v_cmp_gt_f32_e32 vcc, s71, v44
	v_add_f32_e32 v43, -1.0, v42
	v_sub_f32_e32 v45, v43, v42
	v_subbrev_co_u32_e32 v48, vcc, 0, v40, vcc
	v_sub_u32_e32 v40, 0, v48
	v_sub_f32_e32 v43, v39, v43
	v_add_f32_e32 v45, 1.0, v45
	v_ldexp_f32 v41, v42, v40
	v_add_f32_e32 v43, v43, v45
	v_add_f32_e32 v42, -1.0, v41
	v_add_f32_e32 v44, 1.0, v41
	v_ldexp_f32 v40, v43, v40
	v_add_f32_e32 v43, 1.0, v42
	v_add_f32_e32 v45, -1.0, v44
	v_sub_f32_e32 v43, v41, v43
	v_sub_f32_e32 v41, v41, v45
	v_add_f32_e32 v43, v40, v43
	v_add_f32_e32 v40, v40, v41
	v_add_f32_e32 v49, v44, v40
	v_rcp_f32_e32 v51, v49
	v_sub_f32_e32 v41, v49, v44
	v_sub_f32_e32 v50, v40, v41
	v_add_f32_e32 v41, v42, v43
	v_mul_f32_e32 v53, v41, v51
	v_sub_f32_e32 v40, v41, v42
	v_mul_f32_e32 v42, v49, v53
	v_fma_f32 v44, v53, v49, -v42
	v_fmac_f32_e32 v44, v53, v50
	v_sub_f32_e32 v52, v43, v40
	v_add_f32_e32 v40, v42, v44
	v_sub_f32_e32 v43, v41, v40
	v_pk_add_f32 v[46:47], v[40:41], v[42:43] neg_lo:[0,1] neg_hi:[0,1]
	v_mov_b32_e32 v45, v40
	v_pk_add_f32 v[40:41], v[46:47], v[44:45] neg_lo:[0,1] neg_hi:[0,1]
	s_mov_b32 s71, 0x3f317218
	v_add_f32_e32 v41, v52, v41
	v_add_f32_e32 v40, v40, v41
	v_add_f32_e32 v41, v43, v40
	v_mul_f32_e32 v52, v51, v41
	v_mul_f32_e32 v42, v49, v52
	v_fma_f32 v44, v52, v49, -v42
	v_fmac_f32_e32 v44, v52, v50
	v_sub_f32_e32 v43, v43, v41
	v_add_f32_e32 v49, v40, v43
	v_add_f32_e32 v40, v42, v44
	v_sub_f32_e32 v43, v41, v40
	v_pk_add_f32 v[46:47], v[40:41], v[42:43] neg_lo:[0,1] neg_hi:[0,1]
	v_mov_b32_e32 v45, v40
	v_pk_add_f32 v[40:41], v[46:47], v[44:45] neg_lo:[0,1] neg_hi:[0,1]
	s_nop 0
	v_add_f32_e32 v41, v49, v41
	v_add_f32_e32 v40, v40, v41
	v_add_f32_e32 v41, v53, v52
	v_add_f32_e32 v40, v43, v40
	v_sub_f32_e32 v42, v41, v53
	v_mul_f32_e32 v40, v51, v40
	v_sub_f32_e32 v42, v52, v42
	v_add_f32_e32 v42, v42, v40
	v_add_f32_e32 v44, v41, v42
	v_mul_f32_e32 v45, v44, v44
	v_fmamk_f32 v40, v45, 0x3e9b6dac, v212
	v_fmaak_f32 v95, v45, v40, 0x3f2aaada
	v_cvt_f32_i32_e32 v40, v48
	v_sub_f32_e32 v41, v44, v41
	v_sub_f32_e32 v41, v42, v41
	v_ldexp_f32 v46, v41, 1
	v_mul_f32_e32 v41, v44, v45
	v_ldexp_f32 v43, v44, 1
	v_pk_mul_f32 v[44:45], v[40:41], v[94:95]
	s_nop 0
	v_fma_f32 v42, v40, s71, -v44
	v_fmac_f32_e32 v42, 0xb102e308, v40
	v_pk_add_f32 v[40:41], v[44:45], v[42:43]
	s_mov_b32 s71, 0x7f800000
	v_sub_f32_e32 v43, v41, v43
	v_sub_f32_e32 v43, v45, v43
	v_add_f32_e32 v47, v46, v43
	v_mov_b32_e32 v46, v44
	v_pk_add_f32 v[44:45], v[40:41], v[44:45] neg_lo:[0,1] neg_hi:[0,1]
	v_pk_add_f32 v[48:49], v[40:41], v[46:47]
	v_mov_b32_e32 v43, v40
	v_mov_b32_e32 v45, v49
	v_pk_add_f32 v[50:51], v[42:43], v[44:45] neg_lo:[0,1] neg_hi:[0,1]
	v_pk_add_f32 v[42:43], v[42:43], v[44:45]
	v_mov_b32_e32 v46, v47
	v_pk_add_f32 v[44:45], v[42:43], v[40:41] op_sel:[1,0] op_sel_hi:[0,1] neg_lo:[0,1] neg_hi:[0,1]
	v_pk_add_f32 v[52:53], v[48:49], v[44:45] op_sel_hi:[1,0] neg_lo:[0,1] neg_hi:[0,1]
	v_mov_b32_e32 v48, v49
	v_mov_b32_e32 v49, v43
	v_pk_mov_b32 v[44:45], v[40:41], v[44:45] op_sel:[1,0]
	v_mov_b32_e32 v47, v40
	v_pk_add_f32 v[44:45], v[48:49], v[44:45] neg_lo:[0,1] neg_hi:[0,1]
	v_mov_b32_e32 v52, v50
	v_pk_add_f32 v[40:41], v[46:47], v[44:45] neg_lo:[0,1] neg_hi:[0,1]
	v_mov_b32_e32 v51, v43
	v_pk_add_f32 v[44:45], v[52:53], v[40:41]
	v_cmp_neq_f32_e32 vcc, s71, v39
	v_pk_add_f32 v[46:47], v[44:45], v[44:45] op_sel:[0,1] op_sel_hi:[1,0]
	s_mov_b32 s71, 0x33800000
	v_pk_add_f32 v[42:43], v[42:43], v[46:47] op_sel:[1,0] op_sel_hi:[0,1]
	v_mov_b32_e32 v45, v42
	v_pk_add_f32 v[48:49], v[44:45], v[50:51] neg_lo:[0,1] neg_hi:[0,1]
	v_mov_b32_e32 v41, v46
	v_sub_f32_e32 v43, v44, v48
	v_pk_add_f32 v[40:41], v[40:41], v[48:49] neg_lo:[0,1] neg_hi:[0,1]
	v_sub_f32_e32 v43, v50, v43
	v_add_f32_e32 v40, v40, v43
	v_add_f32_e32 v40, v40, v41
	v_add_f32_e32 v40, v42, v40
	v_cndmask_b32_e32 v40, v225, v40, vcc
	v_cmp_ngt_f32_e32 vcc, -1.0, v39
	s_nop 1
	v_cndmask_b32_e32 v40, v226, v40, vcc
	v_cmp_neq_f32_e32 vcc, -1.0, v39
	s_nop 1
	v_cndmask_b32_e32 v40, v227, v40, vcc
	v_cmp_lt_f32_e64 vcc, |v39|, s71
	s_nop 1
	v_cndmask_b32_e32 v39, v40, v39, vcc

.Lp3pre_332:
	s_or_b64 exec, exec, s[2:3]
	v_mul_f32_e32 v40, 0x3fb8aa3b, v38
	v_rndne_f32_e32 v41, v40
	s_mov_b32 s2, 0x3fb8aa3b
	v_sub_f32_e32 v42, v40, v41
	v_fma_f32 v40, v38, s2, -v40
	v_fmac_f32_e32 v40, 0x32a5705f, v38
	v_add_f32_e32 v40, v42, v40
	v_cvt_i32_f32_e32 v41, v41
	v_exp_f32_e32 v40, v40
	s_mov_b32 s3, 0xc2ce8ed0
	v_cmp_ngt_f32_e32 vcc, s3, v38
	v_mul_f32_e32 v37, 0xbfb8aa3b, v37
	v_ldexp_f32 v40, v40, v41
	s_waitcnt vmcnt(0)
	v_mul_f32_e32 v41, 0x3fb8aa3b, v34
	v_rndne_f32_e32 v42, v41
	v_sub_f32_e32 v43, v41, v42
	v_fma_f32 v41, v34, s2, -v41
	v_fmac_f32_e32 v41, 0x32a5705f, v34
	v_add_f32_e32 v41, v43, v41
	v_exp_f32_e32 v41, v41
	v_cvt_i32_f32_e32 v42, v42
	s_mov_b32 s2, 0x42b17218
	v_cndmask_b32_e32 v40, 0, v40, vcc
	v_cmp_nlt_f32_e32 vcc, s2, v38
	v_ldexp_f32 v41, v41, v42
	v_mul_f32_e32 v36, 0xbfb8aa3b, v36
	v_cndmask_b32_e32 v38, v225, v40, vcc
	v_cmp_ngt_f32_e32 vcc, s3, v34
	v_mul_f32_e64 v40, v39, -v38
	ds_bpermute_b32 v42, v162, v40
	v_cndmask_b32_e32 v41, 0, v41, vcc
	v_cmp_nlt_f32_e32 vcc, s2, v34
	v_readlane_b32 s2, v250, 39
	v_readlane_b32 s3, v250, 40
	v_cndmask_b32_e32 v34, v225, v41, vcc
	v_mul_f32_e64 v41, v35, -v34
	ds_bpermute_b32 v43, v168, v41
	s_waitcnt lgkmcnt(1)
	v_fma_f32 v38, v39, -v38, v42
	v_cndmask_b32_e64 v38, v38, v40, s[2:3]
	v_readlane_b32 s2, v250, 47
	ds_bpermute_b32 v39, v163, v38
	s_waitcnt lgkmcnt(1)
	v_fma_f32 v34, v35, -v34, v43
	v_readlane_b32 s3, v250, 48
	v_exp_f32_e32 v37, v37
	v_exp_f32_e32 v36, v36
	v_cndmask_b32_e64 v34, v34, v41, s[2:3]
	ds_bpermute_b32 v35, v169, v34
	v_readlane_b32 s2, v250, 41
	s_waitcnt lgkmcnt(1)
	v_add_f32_e32 v39, v38, v39
	v_readlane_b32 s3, v250, 42
	v_add_f32_e32 v37, 1.0, v37
	s_waitcnt lgkmcnt(0)
	v_add_f32_e32 v35, v34, v35
	v_cndmask_b32_e64 v38, v39, v38, s[2:3]
	v_readlane_b32 s2, v250, 49
	ds_bpermute_b32 v39, v164, v38
	v_readlane_b32 s3, v250, 50
	v_add_f32_e32 v36, 1.0, v36
	v_rcp_f32_e32 v37, v37
	v_cndmask_b32_e64 v34, v34, v35, s[2:3]
	ds_bpermute_b32 v35, v170, v34
	v_readlane_b32 s2, v250, 43
	s_waitcnt lgkmcnt(1)
	v_add_f32_e32 v39, v38, v39
	v_readlane_b32 s3, v250, 44
	v_rcp_f32_e32 v36, v36
	s_waitcnt lgkmcnt(0)
	v_add_f32_e32 v35, v34, v35
	v_cndmask_b32_e64 v38, v39, v38, s[2:3]
	v_readlane_b32 s2, v250, 51
	ds_bpermute_b32 v39, v165, v38
	v_readlane_b32 s3, v250, 52
	s_waitcnt lgkmcnt(0)
	v_add_f32_e32 v39, v38, v39
	v_cndmask_b32_e64 v34, v34, v35, s[2:3]
	ds_bpermute_b32 v35, v171, v34
	v_readlane_b32 s2, v250, 45
	v_readlane_b32 s3, v250, 46
	s_waitcnt lgkmcnt(0)
	v_add_f32_e32 v35, v34, v35
	v_cndmask_b32_e64 v38, v39, v38, s[2:3]
	v_readlane_b32 s2, v250, 53
	v_readlane_b32 s3, v250, 54
	ds_bpermute_b32 v39, v166, v38
	s_waitcnt lgkmcnt(0)
	v_add_f32_e32 v39, v38, v39
	v_cndmask_b32_e64 v34, v34, v35, s[2:3]
	ds_bpermute_b32 v35, v172, v34
	v_readlane_b32 s2, v250, 55
	v_readlane_b32 s3, v250, 56
	v_cndmask_b32_e64 v38, v39, v38, s[54:55]
	ds_bpermute_b32 v39, v167, v38
	s_waitcnt lgkmcnt(1)
	v_add_f32_e32 v35, v34, v35
	v_cndmask_b32_e64 v34, v34, v35, s[2:3]
	ds_bpermute_b32 v35, v173, v34
	s_waitcnt lgkmcnt(1)
	v_add_f32_e32 v39, v38, v39
	v_cndmask_b32_e64 v38, v39, v38, s[66:67]
	s_waitcnt lgkmcnt(0)
	v_add_f32_e32 v35, v34, v35
	v_cndmask_b32_e64 v40, v34, v35, s[66:67]
	v_lshl_add_u64 v[34:35], s[74:75], 0, v[56:57]
	v_add_co_u32_e32 v34, vcc, 0x2b4000, v34
	ds_write2st64_b32 v58, v38, v40 offset0:136 offset1:137
	ds_write2st64_b32 v58, v37, v36 offset0:138 offset1:139
	v_addc_co_u32_e32 v35, vcc, 0, v35, vcc
	global_store_dword v[34:35], v38, off
	global_store_dword v[34:35], v40, off offset:256
	global_store_dword v[34:35], v37, off offset:512
	global_store_dword v[34:35], v36, off offset:768
	s_waitcnt lgkmcnt(0)
	s_barrier
	s_branch .LBB0_313

.LBB0_327:
	s_or_b64 exec, exec, s[2:3]
	v_readlane_b32 s2, v250, 10
	v_readlane_b32 s3, v250, 11
	s_andn2_b64 vcc, exec, s[2:3]
	s_cbranch_vccnz .LBB0_333
	s_lshr_b32 s2, s53, 8
	s_lshl_b32 s2, s2, 10
	s_add_i32 s2, s2, 0x1c200
	v_add_u32_e32 v34, s2, v184
	ds_read2st64_b32 v[36:37], v34 offset0:136 offset1:137
	ds_read2st64_b32 v[38:39], v34 offset0:138 offset1:139
	s_waitcnt lgkmcnt(0)
	ds_write2st64_b32 v184, v36, v37 offset0:136 offset1:137
	ds_write2st64_b32 v184, v38, v39 offset0:138 offset1:139

.Lp4n_nocwn_A:
	s_cmp_lt_u32 s99, 61
	s_cbranch_scc0 .Lp4n_premid_A
	s_add_u32 s46, s99, 3
	s_nop 3
	v_readlane_b32 s8, v221, s46
	v_readlane_b32 s88, v222, s46
	v_readlane_b32 s20, v223, s46
	v_readlane_b32 s47, v224, s46
	v_readlane_b32 s76, v225, s46
	v_readlane_b32 s77, v226, s46
	v_readlane_b32 s22, v228, s46
	v_readlane_b32 s44, v220, s46
	s_mov_b32 s9, 0
	s_add_u32 s88, s72, s88
	s_addc_u32 s89, s73, 0
	s_nop 1
	v_lshl_add_u64 v[26:27], v[152:153], 0, s[8:9]
	v_add_co_u32_e32 v30, vcc, s49, v26
	v_lshl_add_u64 v[34:35], s[88:89], 0, v[118:119]
	s_nop 0
	v_addc_co_u32_e32 v31, vcc, 0, v27, vcc
	v_add_co_u32_e32 v38, vcc, 0x10000, v34
	v_lshl_add_u64 v[42:43], v[154:155], 0, s[8:9]
	s_nop 0
	v_addc_co_u32_e32 v39, vcc, 0, v35, vcc
	v_add_co_u32_e32 v46, vcc, 0x2000, v42
	global_load_dwordx4 v[26:29], v[26:27], off
	s_nop 0
	global_load_dwordx4 v[30:33], v[30:31], off
	v_addc_co_u32_e32 v47, vcc, 0, v43, vcc
	global_load_dwordx4 v[34:37], v[34:35], off
	s_nop 0
	global_load_dwordx4 v[38:41], v[38:39], off
	s_nop 0
	global_load_dwordx4 v[42:45], v[42:43], off
	s_nop 0
	global_load_dwordx4 v[46:49], v[46:47], off
	s_ashr_i32 s89, s20, 31
	s_add_u32 s88, s0, s20
	s_addc_u32 s89, s1, s89
	s_bfe_u32 s45, s44, 0x60016
	s_cmp_eq_u32 s45, 0
	s_cbranch_scc1 .Lp4n_vedge_A
	s_bfe_u32 s45, s44, 0x10015
	s_cmp_lg_u32 s45, 0
	s_cbranch_scc1 .Lp4n_vedge_A
	global_load_dwordx2 v[128:129], v120, s[88:89]
	s_add_u32 s90, s88, 0x3000
	s_addc_u32 s91, s89, 0
	global_load_dwordx2 v[130:131], v120, s[90:91]
	s_add_u32 s90, s88, 0x6000
	s_addc_u32 s91, s89, 0
	global_load_dwordx2 v[132:133], v120, s[90:91]
	s_add_u32 s90, s88, 0x9000
	s_addc_u32 s91, s89, 0
	global_load_dwordx2 v[136:137], v120, s[90:91]
	s_branch .Lp4n_vdone_A
.Lp4n_vedge_A:
	v_add_u32_e32 v102, s22, v160
	v_cmp_le_i32_e32 vcc, s76, v102
	v_cmp_gt_i32_e64 s[8:9], s77, v102
	v_mov_b32_e32 v130, v158
	v_mov_b32_e32 v131, v158
	s_and_b64 s[90:91], vcc, s[8:9]
	v_lshl_add_u64 v[102:103], s[88:89], 0, v[120:121]
	v_mov_b64_e32 v[128:129], v[130:131]
	s_and_saveexec_b64 s[8:9], s[90:91]
	s_cbranch_execz .Lp4n_v0_A
	global_load_dwordx2 v[128:129], v[102:103], off

.Lp4n_vdone_A:
	s_add_u32 s8, s30, s47
	s_addc_u32 s9, s31, 0
	v_lshl_add_u64 v[102:103], s[8:9], 0, v[122:123]
	global_load_dword v175, v[102:103], off offset:512
	v_mov_b32_e32 v177, 0
	v_mov_b32_e32 v176, 0
	s_and_saveexec_b64 s[20:21], s[4:5]
	s_cbranch_execz .Lp4n_gdone_A
	v_lshl_add_u64 v[102:103], s[8:9], 0, v[124:125]
	global_load_dword v176, v[102:103], off
	global_load_dword v177, v[102:103], off offset:512

.Lp4n_nocwn_B:
	s_cmp_lt_u32 s99, 61
	s_cbranch_scc0 .Lp4n_premid_B
	s_add_u32 s46, s99, 3
	s_nop 3
	v_readlane_b32 s8, v221, s46
	v_readlane_b32 s88, v222, s46
	v_readlane_b32 s20, v223, s46
	v_readlane_b32 s47, v224, s46
	v_readlane_b32 s76, v225, s46
	v_readlane_b32 s77, v226, s46
	v_readlane_b32 s22, v228, s46
	v_readlane_b32 s44, v220, s46
	s_mov_b32 s9, 0
	s_add_u32 s88, s72, s88
	s_addc_u32 s89, s73, 0
	s_nop 1
	v_lshl_add_u64 v[50:51], v[152:153], 0, s[8:9]
	v_add_co_u32_e32 v54, vcc, s49, v50
	v_lshl_add_u64 v[58:59], s[88:89], 0, v[118:119]
	s_nop 0
	v_addc_co_u32_e32 v55, vcc, 0, v51, vcc
	v_add_co_u32_e32 v62, vcc, 0x10000, v58
	v_lshl_add_u64 v[66:67], v[154:155], 0, s[8:9]
	s_nop 0
	v_addc_co_u32_e32 v63, vcc, 0, v59, vcc
	v_add_co_u32_e32 v70, vcc, 0x2000, v66
	global_load_dwordx4 v[50:53], v[50:51], off
	s_nop 0
	global_load_dwordx4 v[54:57], v[54:55], off
	v_addc_co_u32_e32 v71, vcc, 0, v67, vcc
	global_load_dwordx4 v[58:61], v[58:59], off
	s_nop 0
	global_load_dwordx4 v[62:65], v[62:63], off
	s_nop 0
	global_load_dwordx4 v[66:69], v[66:67], off
	s_nop 0
	global_load_dwordx4 v[70:73], v[70:71], off
	s_ashr_i32 s89, s20, 31
	s_add_u32 s88, s0, s20
	s_addc_u32 s89, s1, s89
	s_bfe_u32 s45, s44, 0x60016
	s_cmp_eq_u32 s45, 0
	s_cbranch_scc1 .Lp4n_vedge_B
	s_bfe_u32 s45, s44, 0x10015
	s_cmp_lg_u32 s45, 0
	s_cbranch_scc1 .Lp4n_vedge_B
	global_load_dwordx2 v[134:135], v120, s[88:89]
	s_add_u32 s90, s88, 0x3000
	s_addc_u32 s91, s89, 0
	global_load_dwordx2 v[138:139], v120, s[90:91]
	s_add_u32 s90, s88, 0x6000
	s_addc_u32 s91, s89, 0
	global_load_dwordx2 v[140:141], v120, s[90:91]
	s_add_u32 s90, s88, 0x9000
	s_addc_u32 s91, s89, 0
	global_load_dwordx2 v[142:143], v120, s[90:91]
	s_branch .Lp4n_vdone_B
.Lp4n_vedge_B:
	v_add_u32_e32 v2, s22, v160
	v_cmp_le_i32_e32 vcc, s76, v2
	v_cmp_gt_i32_e64 s[8:9], s77, v2
	v_mov_b32_e32 v138, v158
	v_mov_b32_e32 v139, v158
	s_and_b64 s[90:91], vcc, s[8:9]
	v_lshl_add_u64 v[2:3], s[88:89], 0, v[120:121]
	v_mov_b64_e32 v[134:135], v[138:139]
	s_and_saveexec_b64 s[8:9], s[90:91]
	s_cbranch_execz .Lp4n_v0_B
	global_load_dwordx2 v[134:135], v[2:3], off

.Lp4n_vdone_B:
	s_add_u32 s8, s30, s47
	s_addc_u32 s9, s31, 0
	v_lshl_add_u64 v[2:3], s[8:9], 0, v[122:123]
	global_load_dword v181, v[2:3], off offset:512
	v_mov_b32_e32 v185, 0
	v_mov_b32_e32 v184, 0
	s_and_saveexec_b64 s[20:21], s[4:5]
	s_cbranch_execz .Lp4n_gdone_B
	v_lshl_add_u64 v[2:3], s[8:9], 0, v[124:125]
	global_load_dword v184, v[2:3], off
	global_load_dword v185, v[2:3], off offset:512
